# v91 code with unreachable padding so that every hot loop head has the same address modulo 256 as in v88
# speedup vs baseline: 1.0007x; 1.0007x over previous
; DI int get_tid() { int t = threadIdx.x; asm volatile("" : "+v"(t)); return t; }
; #define PH_BEGIN(n) if (ph_lo <= (n) && (n) < ph_hi) { LAUNDER(q); char* ws = q.ws; (void)ws;
; DI void attn_diff_unit(const Params& p, int li, int b, int h, int qb, char* smem, bool pre, int nh, bool has_next) {
;     ...
;     const float lam = ((const float*)(p.ws + TB_LAM))[li];
;     const int layer = 2 * li + 1;
;     const float linit = 0.8f - 0.6f * expf(-0.3f * (float)layer);
; __global__ void __launch_bounds__(512) mega(Params p, int ph_lo, int ph_hi) {
;     ...
;       PH_BEGIN(pb + 3)
;         if (jx < nx) {
;           const int half = get_tid() >> 8;
;           char* sm = smem + half * ATT_HALF;
; #pragma unroll 1
;           for (int u = jx; u < 256; u += nx) attn_diff_unit(q, li, xcd, u >> 5, u & 31, smem, u != jx, (u + nx) >> 5, u + nx < 256);
.LBB0_556:
	v_readlane_b32 s2, v237, 8
	s_or_b32 s4, s2, 4
	v_readlane_b32 s10, v241, 29
	v_readlane_b32 s11, v241, 30
	s_cmp_gt_i32 s10, s4
	s_cselect_b64 s[2:3], -1, 0
	s_cmp_ge_i32 s4, s11
	s_cselect_b64 s[10:11], -1, 0
	s_or_b64 s[2:3], s[2:3], s[10:11]
	s_and_b64 vcc, exec, s[2:3]
	s_mov_b64 s[2:3], 0
	s_mov_b64 s[4:5], 0
	v_writelane_b32 v237, s2, 9
	s_nop 1
	v_writelane_b32 v237, s3, 10
	s_cbranch_vccnz .LBB0_652
	v_readlane_b32 s10, v240, 22
	v_readlane_b32 s11, v240, 23
	s_mov_b64 s[2:3], 0
	s_andn2_b64 vcc, exec, s[10:11]
	s_cbranch_vccnz .LBB0_598
	v_readlane_b32 s10, v240, 24
	v_readlane_b32 s11, v240, 25
	v_mov_b32_e32 v0, v182
	s_andn2_b64 vcc, exec, s[10:11]
	s_cbranch_vccnz .LBB0_598
	v_readlane_b32 s10, v241, 1
	v_readlane_b32 s11, v241, 2
	s_add_u32 s18, s10, s2
	s_addc_u32 s19, s11, s3
	s_add_u32 s10, s18, 0xa3a8100
	s_addc_u32 s11, s19, 0
	s_add_u32 s12, s18, 0xe3a8100
	s_addc_u32 s13, s19, 0
	s_add_u32 s14, s18, 0x123a8100
	s_addc_u32 s15, s19, 0
	v_cvt_f32_u32_e32 v0, s51
	s_add_u32 s16, s18, 0x63a8100
	v_readlane_b32 s20, v237, 4
	s_addc_u32 s17, s19, 0
	v_readlane_b32 s21, v237, 5
	s_add_u32 s9, s18, 0x5fa0000
	s_mov_b32 s21, s25
	s_addc_u32 s38, s19, 0
	s_lshl_b64 s[2:3], s[20:21], 2
	v_mul_f32_e32 v0, 0xbe99999a, v0
	s_add_u32 s2, s18, s2
	s_waitcnt lgkmcnt(0)
	v_mul_f32_e32 v1, 0x3fb8aa3b, v0
	s_mov_b32 s18, 0x3fb8aa3b
	v_fma_f32 v2, v0, s18, -v1
	v_rndne_f32_e32 v3, v1
	v_fmac_f32_e32 v2, 0x32a5705f, v0
	v_sub_f32_e32 v1, v1, v3
	v_add_f32_e32 v1, v1, v2
	v_exp_f32_e32 v1, v1
	v_cvt_i32_f32_e32 v2, v3
	s_addc_u32 s3, s19, s3
	s_add_u32 s18, s2, 0x5fa4000
	s_mov_b32 s2, 0xc2ce8ed0
	v_ldexp_f32 v1, v1, v2
	v_cmp_ngt_f32_e32 vcc, s2, v0
	s_mov_b32 s2, 0x42b17218
	v_readlane_b32 s40, v241, 31
	v_cndmask_b32_e32 v1, 0, v1, vcc
	v_cmp_nlt_f32_e32 vcc, s2, v0
	s_mov_b32 s2, s20
	s_addc_u32 s19, s3, 0
	v_writelane_b32 v237, s2, 4
	s_lshl_b32 s24, s20, 7
	v_readlane_b32 s50, v241, 41
	v_readlane_b32 s51, v241, 42
	v_readlane_b32 s54, v241, 45
	v_readlane_b32 s55, v241, 46
	v_cndmask_b32_e32 v0, v191, v1, vcc
	v_writelane_b32 v237, s3, 5
	s_lshl_b64 s[2:3], s[24:25], 2
	s_mov_b64 s[50:51], s[54:55]
	v_fmamk_f32 v0, v0, 0x3f19999a, v189
	s_add_u32 s20, s50, s2
	v_add_f32_e32 v152, 1.0, v0
	s_addc_u32 s21, s51, s3
	v_readlane_b32 s51, v237, 11
	v_readlane_b32 s39, v238, 32
	s_mov_b32 s40, s86
	v_readlane_b32 s41, v241, 32
	v_readlane_b32 s42, v241, 33
	v_readlane_b32 s43, v241, 34
	v_readlane_b32 s44, v241, 35
	v_readlane_b32 s45, v241, 36
	v_readlane_b32 s46, v241, 37
	v_readlane_b32 s47, v241, 38
	v_readlane_b32 s48, v241, 39
	v_readlane_b32 s49, v241, 40
	v_readlane_b32 s52, v241, 43
	v_readlane_b32 s53, v241, 44
	s_branch .LBB0_561
	s_nop 0
	s_nop 0
	s_nop 0
	s_nop 0
	s_nop 0
	s_nop 0
	s_nop 0
	s_nop 0
	s_nop 0
	s_nop 0
	s_nop 0
	s_nop 0
	s_nop 0
	s_nop 0
	s_nop 0
	s_nop 0
	s_nop 0
	s_nop 0
	s_nop 0
	s_nop 0
	s_nop 0
	s_nop 0
	s_nop 0
	s_nop 0
	s_nop 0
	s_nop 0
	s_nop 0
	s_nop 0
	s_nop 0
	s_nop 0
	s_nop 0
	s_nop 0
	s_nop 0
	s_nop 0
	s_nop 0
	s_nop 0
	s_nop 0
	s_nop 0
	s_nop 0
	s_nop 0
	s_nop 0
	s_nop 0
	s_nop 0
	s_nop 0
	s_nop 0
	s_nop 0
	s_nop 0
	s_nop 0
	s_nop 0
	s_nop 0
	s_nop 0
	s_nop 0
	s_nop 0
	s_nop 0
	s_nop 0
	s_nop 0
	s_nop 0
	s_nop 0

; #define PG8_STAGE(bufoff, gbase, voff) do { _Pragma("unroll") for (int _i = 0; _i < 2; ++_i) \
;     __builtin_amdgcn_global_load_lds((const unsigned*)((const char*)(gbase) + (voff)[_i]), (LAS unsigned*)(lds + (bufoff) + ldsw + _i * 8192), 16, 0, 0); } while (0)
; #define PG8_WAIT_V(n) asm volatile("s_waitcnt vmcnt(" #n ")" ::: "memory")
; #define PG8_BAR __builtin_amdgcn_s_barrier()
; template <class Epi, class Sched>
; DI void gemm_phase(LAS unsigned char* lds, const Gemm g, const Sched& S, const Epi& E) {
;     ...
;   unsigned voffA[2], voffB[2];
; #pragma unroll
;   for (int i = 0; i < 2; ++i) { int R, C; stage_rc(tid * 16 + i * 8192, R, C); const int Rb = Epi::PERM ? ((R & ~31) + perm32(R & 31)) : R;
;     voffA[i] = (unsigned)(R * K + C) * 2u; voffB[i] = (unsigned)(Rb * K + C) * 2u; }
;   const size_t kstep = (size_t)(BK * 2);
;   const size_t hstep = (size_t)HALF * K * 2;
;   const size_t tstep = 2 * hstep;
;   const unsigned ldsw = (unsigned)wid * 1024u;
;   const int aoff = lds_byte(wr * 64 + fr, fq * 8), boff = lds_byte(wc * 32 + fr, fq * 8);
;     ...
;   Unit cur, nxt; int ui = 0;
;   if (!S.next(0, cur)) return;
;   f32x4 acc[2][2][4][2];
; #pragma unroll
;   for (int a = 0; a < 2; ++a)
; #pragma unroll
;     for (int b = 0; b < 2; ++b)
; #pragma unroll
;       for (int m = 0; m < 4; ++m)
; #pragma unroll
;         for (int n = 0; n < 2; ++n) acc[a][b][m][n] = (f32x4){0.f, 0.f, 0.f, 0.f};
;   bf16x8 At[4][2], B0[2][2], B1[2][2];
;   const char* cA = (const char*)g.A + (size_t)cur.pm * tstep; const char* cB = (const char*)g.Bt + (size_t)cur.pn * tstep;
;   PG8_STAGE(PG8_SB(0, 0), cB, voffB); PG8_STAGE(PG8_SA(0, 0), cA, voffA); PG8_STAGE(PG8_SB(0, 1), cB + hstep, voffB); PG8_STAGE(PG8_SA(0, 1), cA + hstep, voffA);
;   if (wr == 1) PG8_BAR;
;   PG8_WAIT_V(4); PG8_BAR;
;   PG8_STAGE(PG8_SB(1, 0), cB + kstep, voffB); PG8_STAGE(PG8_SA(1, 0), cA + kstep, voffA); PG8_STAGE(PG8_SB(1, 1), cB + hstep + kstep, voffB);
;   PG8_WAIT_V(6); PG8_BAR;
.LBB0_684:
	s_lshl_b32 s2, s2, 5
	s_and_b32 s61, s2, 0x60
	s_lshl_b32 s60, s3, 6
	s_lshl_b32 s14, s3, 13
	s_lshl_b32 s15, s61, 7
	s_add_u32 s2, s10, 0xa3a8100
	s_addc_u32 s3, s11, 0
	s_add_u32 s4, s10, 0x5f20000
	s_addc_u32 s5, s11, 0
	s_add_u32 s6, s10, 0x5f60000
	s_addc_u32 s7, s11, 0
	s_add_i32 m0, s56, 0x18000
	v_lshl_add_u64 v[6:7], v[6:7], 0, s[0:1]
	s_waitcnt vmcnt(4)
	s_barrier
	global_load_lds_dwordx4 v[6:7], off
	v_lshl_add_u64 v[4:5], v[4:5], 0, s[0:1]
	s_add_i32 m0, s56, 0x1a000
	s_add_i32 s62, s56, 0x8000
	s_add_i32 s63, s56, 0xa000
	global_load_lds_dwordx4 v[4:5], off
	v_lshl_add_u64 v[2:3], v[2:3], 0, s[0:1]
	s_mov_b32 m0, s62
	s_add_u32 s12, s22, 0x40080
	global_load_lds_dwordx4 v[2:3], off
	v_lshl_add_u64 v[0:1], v[0:1], 0, s[0:1]
	s_mov_b32 m0, s63
	s_addc_u32 s13, s23, 0
	global_load_lds_dwordx4 v[0:1], off
	s_add_i32 m0, s56, 0x1c000
	v_lshl_add_u64 v[0:1], s[12:13], 0, v[140:141]
	global_load_lds_dwordx4 v[0:1], off
	v_lshl_add_u64 v[0:1], s[12:13], 0, v[136:137]
	s_add_i32 m0, s56, 0x1e000
	s_movk_i32 s12, 0x3c0
	global_load_lds_dwordx4 v[0:1], off
	v_and_b32_e32 v0, 48, v8
	v_lshlrev_b32_e32 v1, 6, v8
	v_and_or_b32 v0, v1, s12, v0
	v_lshlrev_b32_e32 v1, 2, v8
	v_and_b32_e32 v1, 32, v1
	v_bitop3_b32 v2, v0, s14, v1 bitop3:0xde
	v_bitop3_b32 v196, s15, v0, v1 bitop3:0xf6
	v_lshlrev_b32_e32 v0, 14, v13
	v_and_b32_e32 v0, 0xffff8000, v0
	v_lshl_add_u32 v0, v12, 11, v0
	v_and_b32_e32 v1, 1, v13
	v_lshl_or_b32 v0, v1, 6, v0
	v_lshl_add_u32 v146, v14, 1, v0
	v_lshlrev_b32_e32 v0, 14, v9
	v_and_b32_e32 v0, 0xffff8000, v0
	v_readlane_b32 s12, v240, 32
	s_waitcnt vmcnt(6)
	v_lshl_add_u32 v0, v10, 11, v0
	v_and_b32_e32 v1, 1, v9
	v_readlane_b32 s13, v240, 33
	s_add_u32 s10, s10, 0xcba8100
	v_lshl_or_b32 v0, v1, 6, v0
	s_mov_b32 s35, s12
	v_readlane_b32 s12, v240, 30
	s_addc_u32 s11, s11, 0
	v_mov_b32_e32 v147, v145
	v_lshl_add_u32 v148, v11, 1, v0
	v_mov_b32_e32 v149, v145
	s_mov_b32 s34, 0
	v_add_u32_e32 v197, 0, v2
	s_mov_b32 s36, s12
	s_barrier
	v_readlane_b32 s13, v240, 31
	s_branch .LBB0_686
	s_nop 0
	s_nop 0
	s_nop 0
	s_nop 0
	s_nop 0
	s_nop 0
	s_nop 0
	s_nop 0
	s_nop 0
	s_nop 0
	s_nop 0
	s_nop 0
	s_nop 0
	s_nop 0
	s_nop 0
	s_nop 0

; DI int get_tid() { int t = threadIdx.x; asm volatile("" : "+v"(t)); return t; }
; DI void attn_na_unit(const Params& p, int li, int b, int r, int hp, char* smem) {
;     ...
;   char* ks = smem; char* vs = smem + SM_ATT_V; float* tab = (float*)(smem + SM_ATT_TAB);
;   constexpr int KR = 272, VR = 320;
;   const int vbase = tr_base(lane, VR);
;   const int qbk = w & 1, hs = w >> 1, head = 2 * hp + hs;
; __global__ void __launch_bounds__(512) mega(Params p, int ph_lo, int ph_hi) {
;     ...
;           const int half = get_tid() >> 8;
;           char* sm = smem + half * ATT_HALF;
; #pragma unroll 1
;           for (int u = jx; u < 128; u += nx) attn_mla_unit(q, xcd, u >> 4, u & 15, smem, u != jx, (u + nx) >> 4, u + nx < 128);
; #pragma unroll 1
;           for (int up = jx; up < 128; up += nx) { const int u = 2 * up + half; attn_na_unit(q, li, xcd, u >> 2, u & 3, sm); }
.LBB0_1499:
	v_readlane_b32 s10, v237, 12
	v_readlane_b32 s11, v237, 13
	s_add_u32 s6, s10, 0xcda8100
	s_addc_u32 s7, s11, 0
	v_writelane_b32 v237, s6, 14
	v_readlane_b32 s3, v238, 48
	s_waitcnt vmcnt(9)
	v_ashrrev_i32_e32 v116, 8, v136
	v_writelane_b32 v237, s7, 15
	s_add_u32 s6, s10, 0x10da8100
	s_addc_u32 s7, s11, 0
	v_writelane_b32 v237, s6, 16
	s_mov_b32 s2, 0xb000
	v_mov_b32_e32 v0, s3
	v_writelane_b32 v237, s7, 17
	v_readlane_b32 s3, v238, 49
	v_readlane_b32 s6, v237, 4
	s_lshl_b32 s24, s6, 3
	v_mad_i32_i24 v118, v116, s2, v0
	v_mov_b32_e32 v0, s3
	v_readlane_b32 s3, v238, 50
	s_add_u32 s28, s10, 0xeda8100
	v_mad_i32_i24 v119, v116, s2, v0
	v_mov_b32_e32 v0, s3
	v_mad_i32_i24 v117, v116, s2, 0
	s_addc_u32 s29, s11, 0
	s_waitcnt vmcnt(8)
	v_mad_i32_i24 v120, v116, s2, v0
	v_readlane_b32 s2, v238, 40
	s_add_u32 s34, s2, s4
	v_readlane_b32 s2, v238, 41
	s_addc_u32 s35, s2, s5
	v_readlane_b32 s2, v238, 42
	v_readlane_b32 s7, v237, 5
	s_nop 0
	v_add_u16_e32 v121, s2, v116
	s_branch .LBB0_1501
	s_nop 0
	s_nop 0
	s_nop 0
	s_nop 0

; #define PG8_STAGE(bufoff, gbase, voff) do { _Pragma("unroll") for (int _i = 0; _i < 2; ++_i) \
;     __builtin_amdgcn_global_load_lds((const unsigned*)((const char*)(gbase) + (voff)[_i]), (LAS unsigned*)(lds + (bufoff) + ldsw + _i * 8192), 16, 0, 0); } while (0)
; #define PG8_WAIT_V(n) asm volatile("s_waitcnt vmcnt(" #n ")" ::: "memory")
; #define PG8_BAR __builtin_amdgcn_s_barrier()
; template <class Epi, class Sched>
; DI void gemm_phase(LAS unsigned char* lds, const Gemm g, const Sched& S, const Epi& E) {
;     ...
;   unsigned voffA[2], voffB[2];
; #pragma unroll
;   for (int i = 0; i < 2; ++i) { int R, C; stage_rc(tid * 16 + i * 8192, R, C); const int Rb = Epi::PERM ? ((R & ~31) + perm32(R & 31)) : R;
;     voffA[i] = (unsigned)(R * K + C) * 2u; voffB[i] = (unsigned)(Rb * K + C) * 2u; }
;   const size_t kstep = (size_t)(BK * 2);
;   const size_t hstep = (size_t)HALF * K * 2;
;   const size_t tstep = 2 * hstep;
;   const unsigned ldsw = (unsigned)wid * 1024u;
;   const int aoff = lds_byte(wr * 64 + fr, fq * 8), boff = lds_byte(wc * 32 + fr, fq * 8);
;     ...
;   Unit cur, nxt; int ui = 0;
;   if (!S.next(0, cur)) return;
;   f32x4 acc[2][2][4][2];
; #pragma unroll
;   for (int a = 0; a < 2; ++a)
; #pragma unroll
;     for (int b = 0; b < 2; ++b)
; #pragma unroll
;       for (int m = 0; m < 4; ++m)
; #pragma unroll
;         for (int n = 0; n < 2; ++n) acc[a][b][m][n] = (f32x4){0.f, 0.f, 0.f, 0.f};
;   bf16x8 At[4][2], B0[2][2], B1[2][2];
;   const char* cA = (const char*)g.A + (size_t)cur.pm * tstep; const char* cB = (const char*)g.Bt + (size_t)cur.pn * tstep;
;   PG8_STAGE(PG8_SB(0, 0), cB, voffB); PG8_STAGE(PG8_SA(0, 0), cA, voffA); PG8_STAGE(PG8_SB(0, 1), cB + hstep, voffB); PG8_STAGE(PG8_SA(0, 1), cA + hstep, voffA);
;   if (wr == 1) PG8_BAR;
;   PG8_WAIT_V(4); PG8_BAR;
;   PG8_STAGE(PG8_SB(1, 0), cB + kstep, voffB); PG8_STAGE(PG8_SA(1, 0), cA + kstep, voffA); PG8_STAGE(PG8_SB(1, 1), cB + hstep + kstep, voffB);
;   PG8_WAIT_V(6); PG8_BAR;
.LBB0_1635:
	v_readlane_b32 s48, v241, 13
	v_readlane_b32 s49, v241, 14
	s_lshl_b64 s[6:7], s[6:7], 2
	s_mov_b64 s[16:17], s[48:49]
	s_add_u32 s6, s16, s6
	s_addc_u32 s7, s17, s7
	v_readlane_b32 s10, v237, 11
	s_cmp_eq_u32 s10, 0
	s_cselect_b32 s7, s7, 0
	s_cselect_b32 s6, s6, 0
	s_add_u32 s10, s12, 0x61a4100
	s_addc_u32 s11, s13, 0
	s_add_u32 s12, s12, 0x1a3a8100
	s_addc_u32 s13, s13, 0
	s_and_b32 s46, s15, 3
	v_and_b32_e32 v15, 48, v14
	v_lshlrev_b32_e32 v16, 6, v14
	s_movk_i32 s15, 0x3c0
	v_lshlrev_b32_e32 v14, 2, v14
	v_readlane_b32 s50, v241, 15
	s_lshl_b32 s47, s14, 6
	s_lshl_b32 s14, s14, 13
	v_and_or_b32 v15, v16, s15, v15
	v_and_b32_e32 v14, 32, v14
	s_add_i32 m0, s41, 0x18000
	v_lshl_add_u64 v[6:7], v[6:7], 0, s[0:1]
	v_bitop3_b32 v16, v15, s14, v14 bitop3:0xde
	s_lshl_b32 s48, s46, 5
	s_lshl_b32 s14, s46, 12
	s_waitcnt vmcnt(4)
	s_barrier
	global_load_lds_dwordx4 v[6:7], off
	v_lshl_add_u64 v[4:5], v[4:5], 0, s[0:1]
	s_add_i32 m0, s41, 0x1a000
	s_add_i32 s49, s41, 0x8000
	s_add_i32 s50, s41, 0xa000
	v_bitop3_b32 v158, v15, s14, v14 bitop3:0xde
	global_load_lds_dwordx4 v[4:5], off
	v_lshl_add_u64 v[2:3], v[2:3], 0, s[0:1]
	s_mov_b32 m0, s49
	s_add_u32 s14, s4, 0x40080
	global_load_lds_dwordx4 v[2:3], off
	v_lshl_add_u64 v[0:1], v[0:1], 0, s[0:1]
	s_mov_b32 m0, s50
	s_addc_u32 s15, s5, 0
	global_load_lds_dwordx4 v[0:1], off
	s_add_i32 m0, s41, 0x1c000
	v_lshl_add_u64 v[0:1], s[14:15], 0, v[144:145]
	global_load_lds_dwordx4 v[0:1], off
	v_lshl_add_u64 v[0:1], s[14:15], 0, v[136:137]
	s_add_i32 m0, s41, 0x1e000
	s_cmp_lg_u64 s[6:7], 0
	global_load_lds_dwordx4 v[0:1], off
	v_lshlrev_b32_e32 v0, 14, v12
	v_and_b32_e32 v0, 0xffff8000, v0
	v_lshl_add_u32 v0, v11, 11, v0
	v_and_b32_e32 v1, 1, v12
	v_lshl_or_b32 v0, v1, 6, v0
	v_lshl_add_u32 v142, v13, 1, v0
	v_lshlrev_b32_e32 v0, 14, v8
	v_and_b32_e32 v0, 0xffff8000, v0
	s_waitcnt vmcnt(6)
	v_lshl_add_u32 v0, v9, 11, v0
	v_and_b32_e32 v1, 1, v8
	v_lshl_or_b32 v0, v1, 6, v0
	v_readlane_b32 s16, v240, 53
	s_mov_b32 s45, 0
	s_cselect_b64 s[14:15], -1, 0
	v_mov_b32_e32 v143, v145
	v_lshl_add_u32 v146, v10, 1, v0
	v_mov_b32_e32 v147, v145
	v_add_u32_e32 v159, 0, v16
	v_readlane_b32 s24, v240, 46
	s_mov_b32 s34, s16
	v_readlane_b32 s51, v241, 16
	v_readlane_b32 s52, v241, 17
	v_readlane_b32 s53, v241, 18
	v_readlane_b32 s54, v241, 19
	v_readlane_b32 s55, v241, 20
	v_readlane_b32 s56, v241, 21
	v_readlane_b32 s57, v241, 22
	v_readlane_b32 s58, v241, 23
	v_readlane_b32 s59, v241, 24
	v_readlane_b32 s60, v241, 25
	v_readlane_b32 s61, v241, 26
	v_readlane_b32 s62, v241, 27
	v_readlane_b32 s63, v241, 28
	s_barrier
	v_readlane_b32 s17, v240, 54
	s_branch .LBB0_1637
	s_nop 0
	s_nop 0
	s_nop 0
	s_nop 0
	s_nop 0
	s_nop 0
	s_nop 0
